# scan loader steady loop trimmed: 16 dead register copies removed, IEEE sqrt refinement -> v_sqrt_f32, IEEE -1/x -> v_rcp_f32 (41 instructions per chunk)
# speedup vs baseline: 1.0035x; 1.0035x over previous
; __device__ __forceinline__ void phase_scan(CParams& p, LAS unsigned char* lds) {
;     ...
;             auto load_chunk = [&](int c, LRaw& L) {
;                 const int t = c * SCH + lw * 8 + sl; const size_t m = m0 + t, mp = t > 0 ? m - 1 : m;
;                 const bf16_t* pc = p.pr + m * DSH + ch0; const bf16_t* pp = p.pr + mp * DSH + ch0;
;                 L.r0 = *(const u32x4*)pc; L.k0 = *(const u32x4*)(pc + 1024); L.v0 = *(const u32x4*)(pc + 2048);
;                 L.r1 = *(const u32x4*)pp; L.k1 = *(const u32x4*)(pp + 1024); L.v1 = *(const u32x4*)(pp + 2048);
;                 L.a = *(const u32x4*)(p.abuf + m * 1024 + ch0); L.e = *(const u32x4*)(p.ebuf + m * 1024 + ch0);
;             };
;     ...
;             for (int c = 0; c < nch; ++c) {
;                 const int nst = (T - c * SCH) < SCH ? (T - c * SCH) : SCH;
;                 if (c + 1 < nch) {
;                     cur = nxt;
;                     if (c + 2 < nch) load_chunk(c + 2, nxt);
;                     process(c + 1, cur);
.LBB0_172:
	s_waitcnt vmcnt(9)
	s_waitcnt vmcnt(8)
	s_waitcnt vmcnt(5)
	s_waitcnt vmcnt(4)
	s_waitcnt vmcnt(3)
	s_waitcnt vmcnt(2)
	s_andn2_b64 vcc, exec, s[12:13]
	s_cbranch_vccnz .LBB0_174
	v_add_u32_e32 v0, 64, v126
	v_ashrrev_i32_e32 v1, 31, v0
	v_cmp_lt_i32_e32 vcc, 0, v0
	v_lshl_add_u64 v[4:5], s[48:49], 0, v[0:1]
	v_mov_b32_e32 v127, v126
	v_cndmask_b32_e64 v0, 0, 1, vcc
	v_sub_co_u32_e32 v6, vcc, v4, v0
	v_mad_u64_u32 v[0:1], s[12:13], v4, s85, v[112:113]
	v_mad_u64_u32 v[6:7], s[12:13], v6, s85, v[112:113]
	v_subbrev_co_u32_e32 v9, vcc, 0, v5, vcc
	v_mov_b32_e32 v2, v1
	v_mov_b32_e32 v8, v7
	v_mad_u64_u32 v[2:3], s[12:13], v5, s85, v[2:3]
	v_mad_u64_u32 v[8:9], s[12:13], v9, s85, v[8:9]
	v_mov_b32_e32 v1, v2
	s_movk_i32 s12, 0x1000
	global_load_dwordx4 v[28:31], v[0:1], off
	global_load_dwordx4 v[20:23], v[0:1], off offset:2048
	v_add_co_u32_e32 v0, vcc, s12, v0
	v_mov_b32_e32 v7, v8
	s_nop 0
	v_addc_co_u32_e32 v1, vcc, 0, v2, vcc
	global_load_dwordx4 v[16:19], v[6:7], off
	global_load_dwordx4 v[12:15], v[6:7], off offset:2048
	v_add_co_u32_e32 v6, vcc, 0x1000, v6
	v_lshlrev_b64 v[4:5], 11, v[4:5]
	s_nop 0
	v_addc_co_u32_e32 v7, vcc, 0, v8, vcc
	global_load_dwordx4 v[0:3], v[0:1], off
	s_nop 0
	global_load_dwordx4 v[8:11], v[6:7], off
	v_lshl_add_u64 v[6:7], v[114:115], 0, v[4:5]
	v_lshl_add_u64 v[4:5], v[116:117], 0, v[4:5]
	global_load_dwordx4 v[24:27], v[6:7], off
	s_nop 0
	global_load_dwordx4 v[4:7], v[4:5], off

; #define LAS __attribute__((address_space(3)))
; __device__ __forceinline__ float reduce8(float x) { x += dppf<0xB1>(x); x += dppf<0x4E>(x); x += dppf<0x141>(x); return x; }
; __device__ __forceinline__ void phase_scan(CParams& p, LAS unsigned char* lds) {
;     ...
;                 r0 = r0 + (pr0 - r0) * mur0; r1 = r1 + (pr1 - r1) * mur1; k0 = k0 + (pk0 - k0) * muk0; k1 = k1 + (pk1 - k1) * muk1; v0 = v0 + (pv0 - v0) * muv0; v1 = v1 + (pv1 - v1) * muv1;
;                 f32x4 w0, w1;
; #pragma unroll
;                 for (int i = 0; i < 4; ++i) { w0[i] = __expf(-e0[i]); w1[i] = __expf(-e1[i]); }
;                 f32x4 kk0 = k0 * kkc0, kk1 = k1 * kkc1;
;                 const float n2 = reduce8(dot4(kk0, kk0) + dot4(kk1, kk1)), inv = 1.f / fmaxf(sqrtf(n2), 1e-12f);
;                 kk0 = kk0 * inv; kk1 = kk1 * inv;
;                 const f32x4 k20 = k0 * (1.f + (a0 - 1.f) * kac0), k21 = k1 * (1.f + (a1 - 1.f) * kac1), bb0 = kk0 * a0, bb1 = kk1 * a1;
;                 const float rks = reduce8(dot4(r0 * k20, rkc0) + dot4(r1 * k21, rkc1));
;                 if (g == 0 && hf == 0 && t < T) p.rk[m * 16 + h] = rks;
;                 LAS float* so = (LAS float*)(lds + (c & 1) * SBUF + sidx * 1536) + 8 * g;
;                 *(LAS f32x4*)(so) = r0; *(LAS f32x4*)(so + 4) = r1; *(LAS f32x4*)(so + 64) = w0; *(LAS f32x4*)(so + 68) = w1;
;                 *(LAS f32x4*)(so + 128) = k20; *(LAS f32x4*)(so + 132) = k21; *(LAS f32x4*)(so + 192) = -kk0; *(LAS f32x4*)(so + 196) = -kk1;
;                 *(LAS f32x4*)(so + 256) = bb0; *(LAS f32x4*)(so + 260) = bb1; *(LAS f32x4*)(so + 320) = v0; *(LAS f32x4*)(so + 324) = v1;
.LBB0_176:
	s_or_b64 exec, exec, s[12:13]
	v_lshlrev_b32_e32 v170, 16, v88
	v_and_b32_e32 v171, 0xffff0000, v88
	v_lshlrev_b32_e32 v88, 16, v86
	v_and_b32_e32 v86, 0xffff0000, v86
	v_mul_f32_e32 v86, 0xbfb8aa3b, v86
	v_lshlrev_b32_e32 v172, 16, v89
	v_and_b32_e32 v173, 0xffff0000, v89
	v_exp_f32_e32 v89, v86
	v_lshlrev_b32_e32 v86, 16, v87
	v_mul_f32_e32 v86, 0xbfb8aa3b, v86
	v_lshlrev_b32_e32 v138, 16, v90
	v_and_b32_e32 v139, 0xffff0000, v90
	v_exp_f32_e32 v90, v86
	v_and_b32_e32 v86, 0xffff0000, v87
	v_mul_f32_e32 v86, 0xbfb8aa3b, v86
	v_lshlrev_b32_e32 v180, 16, v91
	v_and_b32_e32 v181, 0xffff0000, v91
	v_exp_f32_e32 v91, v86
	v_lshlrev_b32_e32 v86, 16, v84
	v_and_b32_e32 v84, 0xffff0000, v84
	v_mul_f32_e32 v84, 0xbfb8aa3b, v84
	v_exp_f32_e32 v145, v84
	v_lshlrev_b32_e32 v84, 16, v85
	v_mul_f32_e32 v84, 0xbfb8aa3b, v84
	v_mul_f32_e32 v86, 0xbfb8aa3b, v86
	v_exp_f32_e32 v146, v84
	v_add_f32_e32 v84, v142, v143
	v_exp_f32_e32 v144, v86
	v_and_b32_e32 v85, 0xffff0000, v85
	v_mul_f32_e32 v85, 0xbfb8aa3b, v85
	v_sqrt_f32_e32 v84, v84
	v_exp_f32_e32 v147, v85
	s_bitcmp1_b32 s33, 0
	v_mul_f32_e32 v88, 0xbfb8aa3b, v88
	v_exp_f32_e32 v88, v88
	v_lshlrev_b32_e32 v86, 16, v82
	v_and_b32_e32 v87, 0xffff0000, v82
	v_max_f32_e32 v182, 0x2b8cbccc, v84
	v_lshlrev_b32_e32 v82, 16, v83
	v_and_b32_e32 v83, 0xffff0000, v83
	v_sub_f32_e32 v84, v180, v82
	v_sub_f32_e32 v85, v181, v83
	v_sub_f32_e32 v139, v139, v87
	v_sub_f32_e32 v138, v138, v86
	v_pk_fma_f32 v[84:85], v[50:51], v[84:85], v[82:83]
	v_pk_fma_f32 v[82:83], v[48:49], v[138:139], v[86:87]
	v_lshlrev_b32_e32 v86, 16, v80
	v_and_b32_e32 v87, 0xffff0000, v80
	v_lshlrev_b32_e32 v80, 16, v81
	v_and_b32_e32 v81, 0xffff0000, v81
	v_sub_f32_e32 v143, v173, v81
	v_sub_f32_e32 v142, v172, v80
	v_pk_fma_f32 v[172:173], v[54:55], v[142:143], v[80:81]
	v_sub_f32_e32 v139, v171, v87
	v_sub_f32_e32 v138, v170, v86
	v_pk_fma_f32 v[170:171], v[52:53], v[138:139], v[86:87]
	v_rcp_f32_e64 v80, -v182
	s_cselect_b32 s12, 0xc000, 0
	v_pk_mul_f32 v[136:137], v[136:137], v[80:81] op_sel_hi:[1,0]
	v_pk_mul_f32 v[134:135], v[134:135], v[80:81] op_sel_hi:[1,0]
	v_pk_mul_f32 v[132:133], v[132:133], v[80:81] op_sel_hi:[1,0]
	v_pk_mul_f32 v[130:131], v[130:131], v[80:81] op_sel_hi:[1,0]
	v_add_u32_e32 v80, s12, v175
	v_pk_mul_f32 v[128:129], v[136:137], v[128:129] neg_lo:[1,0] neg_hi:[1,0]
	v_pk_mul_f32 v[126:127], v[134:135], v[126:127] neg_lo:[1,0] neg_hi:[1,0]
	v_pk_mul_f32 v[110:111], v[132:133], v[110:111] neg_lo:[1,0] neg_hi:[1,0]
	v_pk_mul_f32 v[108:109], v[130:131], v[108:109] neg_lo:[1,0] neg_hi:[1,0]
	ds_write_b128 v80, v[92:95]
	ds_write_b128 v80, v[96:99] offset:16
	ds_write_b128 v80, v[144:147] offset:256
	ds_write_b128 v80, v[88:91] offset:272
	ds_write_b128 v80, v[100:103] offset:512
	ds_write_b128 v80, v[104:107] offset:528
	ds_write_b128 v80, v[130:133] offset:768
	ds_write_b128 v80, v[134:137] offset:784
	ds_write_b128 v80, v[108:111] offset:1024
	ds_write_b128 v80, v[126:129] offset:1040
	ds_write_b128 v80, v[170:173] offset:1280
	ds_write_b128 v80, v[82:85] offset:1296
